# v38 + no grid barrier between the prologue and the pool-operand phase (the pool phase reads nothing the prologue writes; a workgroup barrier guards the LDS reuse)
# speedup vs baseline: 1.0034x; 1.0034x over previous
.LBB0_438:
	s_cmp_lt_i32 s53, 2
	s_branch .LBB0_538
	s_waitcnt vmcnt(0)
	v_cmp_eq_u32_e32 vcc, 0, v0
	s_waitcnt lgkmcnt(0)
	s_barrier
	s_and_saveexec_b64 s[0:1], vcc
	s_cbranch_execz .LBB0_537
	v_mov_b32_e32 v1, s79
	s_waitcnt vmcnt(0) expcnt(0) lgkmcnt(0)
	ds_read_b32 v3, v1
	ds_read_b32 v1, v1 offset:4
	s_waitcnt lgkmcnt(1)
	v_cmp_ne_u32_e32 vcc, 0, v3
	s_cbranch_vccnz .LBB0_505
	v_readlane_b32 s2, v251, 0
	v_readlane_b32 s3, v251, 1
	s_load_dwordx2 s[4:5], s[2:3], 0x4
	v_readlane_b32 s6, v251, 2
	v_readlane_b32 s7, v251, 3
	s_add_u32 s2, s6, 0x4200
	s_addc_u32 s3, s7, 0
	s_lshl_b32 s10, s55, 8
	s_waitcnt lgkmcnt(0)
	s_mul_i32 s11, s4, s97
	s_add_u32 s12, s6, 0x4400
	s_mov_b32 s9, 0
	s_mul_i32 s11, s11, s5
	s_addc_u32 s13, s7, 0
	v_mov_b32_e32 v2, 0
	s_branch .LBB0_443

.Lp1f_entry:
	s_waitcnt lgkmcnt(0)
	s_barrier
	v_readlane_b32 s8, v251, 48
	v_readlane_b32 s9, v251, 54
	v_readlane_b32 s2, v251, 16
	v_readlane_b32 s3, v251, 17
	v_readlane_b32 s6, v251, 20
	v_readlane_b32 s7, v251, 21
	v_readlane_b32 s4, v251, 2
	v_readlane_b32 s5, v251, 3
	s_nop 1
	s_lshr_b32 s9, s9, 6
	s_lshl_b32 s10, s8, 6
	s_and_b32 s11, s10, 0x1fff
	s_lshr_b32 s52, s9, 1
	s_lshl_b32 s12, 2, s52
	s_lshl_b32 s52, s9, 11
	s_add_u32 s2, s2, s52
	s_addc_u32 s3, s3, 0
	s_add_u32 s6, s6, s52
	s_addc_u32 s7, s7, 0
	s_add_u32 s4, s4, 0x29000000
	s_addc_u32 s5, s5, 0
	s_lshl_b32 s52, s9, 10
	s_add_u32 s4, s4, s52
	s_addc_u32 s5, s5, 0
	v_mbcnt_lo_u32_b32 v1, -1, 0
	v_mbcnt_hi_u32_b32 v1, -1, v1
	v_lshlrev_b32_e32 v3, 3, v1
	v_lshlrev_b32_e32 v1, 4, v1
	global_load_dwordx4 v[4:7], v1, s[6:7]
	global_load_dwordx4 v[8:11], v1, s[6:7] offset:1024
	v_mov_b32_e32 v208, 0
	v_mov_b32_e32 v209, 0
	v_mov_b32_e32 v210, 0
	v_mov_b32_e32 v211, 0
	v_mov_b32_e32 v212, 0
	v_mov_b32_e32 v213, 0
	v_mov_b32_e32 v214, 0
	v_mov_b32_e32 v215, 0
	s_cmp_eq_u32 s11, 0
	s_cbranch_scc1 .Lp1f_nohalo
	s_mov_b32 s13, 0
	s_sub_i32 s14, s10, 16
	s_sub_i32 s15, s11, 16
	s_add_i32 s52, s14, 0
	s_mov_b32 s53, 0
	s_lshl_b64 s[52:53], s[52:53], 14
	s_add_u32 s52, s52, s2
	s_addc_u32 s53, s53, s3
	global_load_dwordx4 v[16:19], v1, s[52:53]
	global_load_dwordx4 v[20:23], v1, s[52:53] offset:1024
	s_add_i32 s52, s14, 1
	s_mov_b32 s53, 0
	s_lshl_b64 s[52:53], s[52:53], 14
	s_add_u32 s52, s52, s2
	s_addc_u32 s53, s53, s3
	global_load_dwordx4 v[24:27], v1, s[52:53]
	global_load_dwordx4 v[28:31], v1, s[52:53] offset:1024
	s_add_i32 s52, s14, 2
	s_mov_b32 s53, 0
	s_lshl_b64 s[52:53], s[52:53], 14
	s_add_u32 s52, s52, s2
	s_addc_u32 s53, s53, s3
	global_load_dwordx4 v[32:35], v1, s[52:53]
	global_load_dwordx4 v[36:39], v1, s[52:53] offset:1024
	s_add_i32 s52, s14, 3
	s_mov_b32 s53, 0
	s_lshl_b64 s[52:53], s[52:53], 14
	s_add_u32 s52, s52, s2
	s_addc_u32 s53, s53, s3
	global_load_dwordx4 v[40:43], v1, s[52:53]
	global_load_dwordx4 v[44:47], v1, s[52:53] offset:1024
	s_add_i32 s52, s14, 4
	s_mov_b32 s53, 0
	s_lshl_b64 s[52:53], s[52:53], 14
	s_add_u32 s52, s52, s2
	s_addc_u32 s53, s53, s3
	global_load_dwordx4 v[48:51], v1, s[52:53]
	global_load_dwordx4 v[52:55], v1, s[52:53] offset:1024
	s_add_i32 s52, s14, 5
	s_mov_b32 s53, 0
	s_lshl_b64 s[52:53], s[52:53], 14
	s_add_u32 s52, s52, s2
	s_addc_u32 s53, s53, s3
	global_load_dwordx4 v[56:59], v1, s[52:53]
	global_load_dwordx4 v[60:63], v1, s[52:53] offset:1024
	s_add_i32 s52, s14, 6
	s_mov_b32 s53, 0
	s_lshl_b64 s[52:53], s[52:53], 14
	s_add_u32 s52, s52, s2
	s_addc_u32 s53, s53, s3
	global_load_dwordx4 v[64:67], v1, s[52:53]
	global_load_dwordx4 v[68:71], v1, s[52:53] offset:1024
	s_add_i32 s52, s14, 7
	s_mov_b32 s53, 0
	s_lshl_b64 s[52:53], s[52:53], 14
	s_add_u32 s52, s52, s2
	s_addc_u32 s53, s53, s3
	global_load_dwordx4 v[72:75], v1, s[52:53]
	global_load_dwordx4 v[76:79], v1, s[52:53] offset:1024
	s_waitcnt vmcnt(0)
	v_mul_f32_e32 v80, v16, v16
	v_fmac_f32_e32 v80, v17, v17
	v_fmac_f32_e32 v80, v18, v18
	v_fmac_f32_e32 v80, v19, v19
	v_fmac_f32_e32 v80, v20, v20
	v_fmac_f32_e32 v80, v21, v21
	v_fmac_f32_e32 v80, v22, v22
	v_fmac_f32_e32 v80, v23, v23
	v_mul_f32_e32 v81, v24, v24
	v_fmac_f32_e32 v81, v25, v25
	v_fmac_f32_e32 v81, v26, v26
	v_fmac_f32_e32 v81, v27, v27
	v_fmac_f32_e32 v81, v28, v28
	v_fmac_f32_e32 v81, v29, v29
	v_fmac_f32_e32 v81, v30, v30
	v_fmac_f32_e32 v81, v31, v31
	v_mul_f32_e32 v82, v32, v32
	v_fmac_f32_e32 v82, v33, v33
	v_fmac_f32_e32 v82, v34, v34
	v_fmac_f32_e32 v82, v35, v35
	v_fmac_f32_e32 v82, v36, v36
	v_fmac_f32_e32 v82, v37, v37
	v_fmac_f32_e32 v82, v38, v38
	v_fmac_f32_e32 v82, v39, v39
	v_mul_f32_e32 v83, v40, v40
	v_fmac_f32_e32 v83, v41, v41
	v_fmac_f32_e32 v83, v42, v42
	v_fmac_f32_e32 v83, v43, v43
	v_fmac_f32_e32 v83, v44, v44
	v_fmac_f32_e32 v83, v45, v45
	v_fmac_f32_e32 v83, v46, v46
	v_fmac_f32_e32 v83, v47, v47
	v_mul_f32_e32 v84, v48, v48
	v_fmac_f32_e32 v84, v49, v49
	v_fmac_f32_e32 v84, v50, v50
	v_fmac_f32_e32 v84, v51, v51
	v_fmac_f32_e32 v84, v52, v52
	v_fmac_f32_e32 v84, v53, v53
	v_fmac_f32_e32 v84, v54, v54
	v_fmac_f32_e32 v84, v55, v55
	v_mul_f32_e32 v85, v56, v56
	v_fmac_f32_e32 v85, v57, v57
	v_fmac_f32_e32 v85, v58, v58
	v_fmac_f32_e32 v85, v59, v59
	v_fmac_f32_e32 v85, v60, v60
	v_fmac_f32_e32 v85, v61, v61
	v_fmac_f32_e32 v85, v62, v62
	v_fmac_f32_e32 v85, v63, v63
	v_mul_f32_e32 v86, v64, v64
	v_fmac_f32_e32 v86, v65, v65
	v_fmac_f32_e32 v86, v66, v66
	v_fmac_f32_e32 v86, v67, v67
	v_fmac_f32_e32 v86, v68, v68
	v_fmac_f32_e32 v86, v69, v69
	v_fmac_f32_e32 v86, v70, v70
	v_fmac_f32_e32 v86, v71, v71
	v_mul_f32_e32 v87, v72, v72
	v_fmac_f32_e32 v87, v73, v73
	v_fmac_f32_e32 v87, v74, v74
	v_fmac_f32_e32 v87, v75, v75
	v_fmac_f32_e32 v87, v76, v76
	v_fmac_f32_e32 v87, v77, v77
	v_fmac_f32_e32 v87, v78, v78
	v_fmac_f32_e32 v87, v79, v79
	s_nop 1
	v_add_f32_dpp v80, v80, v80 quad_perm:[1,0,3,2] row_mask:0xf bank_mask:0xf bound_ctrl:1
	v_add_f32_dpp v81, v81, v81 quad_perm:[1,0,3,2] row_mask:0xf bank_mask:0xf bound_ctrl:1
	v_add_f32_dpp v82, v82, v82 quad_perm:[1,0,3,2] row_mask:0xf bank_mask:0xf bound_ctrl:1
	v_add_f32_dpp v83, v83, v83 quad_perm:[1,0,3,2] row_mask:0xf bank_mask:0xf bound_ctrl:1
	v_add_f32_dpp v84, v84, v84 quad_perm:[1,0,3,2] row_mask:0xf bank_mask:0xf bound_ctrl:1
	v_add_f32_dpp v85, v85, v85 quad_perm:[1,0,3,2] row_mask:0xf bank_mask:0xf bound_ctrl:1
	v_add_f32_dpp v86, v86, v86 quad_perm:[1,0,3,2] row_mask:0xf bank_mask:0xf bound_ctrl:1
	v_add_f32_dpp v87, v87, v87 quad_perm:[1,0,3,2] row_mask:0xf bank_mask:0xf bound_ctrl:1
	s_nop 1
	v_add_f32_dpp v80, v80, v80 quad_perm:[2,3,0,1] row_mask:0xf bank_mask:0xf bound_ctrl:1
	v_add_f32_dpp v81, v81, v81 quad_perm:[2,3,0,1] row_mask:0xf bank_mask:0xf bound_ctrl:1
	v_add_f32_dpp v82, v82, v82 quad_perm:[2,3,0,1] row_mask:0xf bank_mask:0xf bound_ctrl:1
	v_add_f32_dpp v83, v83, v83 quad_perm:[2,3,0,1] row_mask:0xf bank_mask:0xf bound_ctrl:1
	v_add_f32_dpp v84, v84, v84 quad_perm:[2,3,0,1] row_mask:0xf bank_mask:0xf bound_ctrl:1
	v_add_f32_dpp v85, v85, v85 quad_perm:[2,3,0,1] row_mask:0xf bank_mask:0xf bound_ctrl:1
	v_add_f32_dpp v86, v86, v86 quad_perm:[2,3,0,1] row_mask:0xf bank_mask:0xf bound_ctrl:1
	v_add_f32_dpp v87, v87, v87 quad_perm:[2,3,0,1] row_mask:0xf bank_mask:0xf bound_ctrl:1
	s_nop 1
	v_add_f32_dpp v80, v80, v80 row_half_mirror row_mask:0xf bank_mask:0xf bound_ctrl:1
	v_add_f32_dpp v81, v81, v81 row_half_mirror row_mask:0xf bank_mask:0xf bound_ctrl:1
	v_add_f32_dpp v82, v82, v82 row_half_mirror row_mask:0xf bank_mask:0xf bound_ctrl:1
	v_add_f32_dpp v83, v83, v83 row_half_mirror row_mask:0xf bank_mask:0xf bound_ctrl:1
	v_add_f32_dpp v84, v84, v84 row_half_mirror row_mask:0xf bank_mask:0xf bound_ctrl:1
	v_add_f32_dpp v85, v85, v85 row_half_mirror row_mask:0xf bank_mask:0xf bound_ctrl:1
	v_add_f32_dpp v86, v86, v86 row_half_mirror row_mask:0xf bank_mask:0xf bound_ctrl:1
	v_add_f32_dpp v87, v87, v87 row_half_mirror row_mask:0xf bank_mask:0xf bound_ctrl:1
	s_nop 1
	v_add_f32_dpp v80, v80, v80 row_mirror row_mask:0xf bank_mask:0xf bound_ctrl:1
	v_add_f32_dpp v81, v81, v81 row_mirror row_mask:0xf bank_mask:0xf bound_ctrl:1
	v_add_f32_dpp v82, v82, v82 row_mirror row_mask:0xf bank_mask:0xf bound_ctrl:1
	v_add_f32_dpp v83, v83, v83 row_mirror row_mask:0xf bank_mask:0xf bound_ctrl:1
	v_add_f32_dpp v84, v84, v84 row_mirror row_mask:0xf bank_mask:0xf bound_ctrl:1
	v_add_f32_dpp v85, v85, v85 row_mirror row_mask:0xf bank_mask:0xf bound_ctrl:1
	v_add_f32_dpp v86, v86, v86 row_mirror row_mask:0xf bank_mask:0xf bound_ctrl:1
	v_add_f32_dpp v87, v87, v87 row_mirror row_mask:0xf bank_mask:0xf bound_ctrl:1
	v_lshrrev_b32_e32 v12, 6, v1
	v_and_b32_e32 v12, 12, v12
	s_lshl_b32 s52, s9, 4
	s_add_i32 s52, s52, 0
	v_add_u32_e32 v12, s52, v12
	s_mov_b32 exec_lo, 0x10001
	s_mov_b32 exec_hi, 0x10001
	ds_write_b32 v12, v80
	ds_write_b32 v12, v81 offset:128
	ds_write_b32 v12, v82 offset:256
	ds_write_b32 v12, v83 offset:384
	ds_write_b32 v12, v84 offset:512
	ds_write_b32 v12, v85 offset:640
	ds_write_b32 v12, v86 offset:768
	ds_write_b32 v12, v87 offset:896
	s_mov_b64 exec, -1
	s_waitcnt lgkmcnt(0)
	s_barrier
	v_lshrrev_b32_e32 v13, 4, v1
	v_and_b32_e32 v13, 7, v13
	v_lshlrev_b32_e32 v12, 7, v13
	ds_read_b128 v[88:91], v12
	ds_read_b128 v[92:95], v12 offset:16
	ds_read_b128 v[96:99], v12 offset:32
	ds_read_b128 v[100:103], v12 offset:48
	ds_read_b128 v[104:107], v12 offset:64
	ds_read_b128 v[108:111], v12 offset:80
	ds_read_b128 v[112:115], v12 offset:96
	ds_read_b128 v[116:119], v12 offset:112
	s_waitcnt lgkmcnt(0)
	v_add_f32_e32 v14, v88, v89
	v_add_f32_e32 v14, v14, v90
	v_add_f32_e32 v14, v14, v91
	v_add_f32_e32 v14, v14, v92
	v_add_f32_e32 v14, v14, v93
	v_add_f32_e32 v14, v14, v94
	v_add_f32_e32 v14, v14, v95
	v_add_f32_e32 v14, v14, v96
	v_add_f32_e32 v14, v14, v97
	v_add_f32_e32 v14, v14, v98
	v_add_f32_e32 v14, v14, v99
	v_add_f32_e32 v14, v14, v100
	v_add_f32_e32 v14, v14, v101
	v_add_f32_e32 v14, v14, v102
	v_add_f32_e32 v14, v14, v103
	v_add_f32_e32 v14, v14, v104
	v_add_f32_e32 v14, v14, v105
	v_add_f32_e32 v14, v14, v106
	v_add_f32_e32 v14, v14, v107
	v_add_f32_e32 v14, v14, v108
	v_add_f32_e32 v14, v14, v109
	v_add_f32_e32 v14, v14, v110
	v_add_f32_e32 v14, v14, v111
	v_add_f32_e32 v14, v14, v112
	v_add_f32_e32 v14, v14, v113
	v_add_f32_e32 v14, v14, v114
	v_add_f32_e32 v14, v14, v115
	v_add_f32_e32 v14, v14, v116
	v_add_f32_e32 v14, v14, v117
	v_add_f32_e32 v14, v14, v118
	v_add_f32_e32 v14, v14, v119
	v_mov_b32_e32 v221, 0x358637bd
	v_mov_b32_e32 v222, 0x260
	s_mov_b32 s54, 0xf800000
	v_fmamk_f32 v14, v14, 0x39800000, v221
	v_mul_f32_e32 v15, 0x4f800000, v14
	v_cmp_gt_f32_e32 vcc, s54, v14
	s_nop 1
	v_cndmask_b32_e32 v14, v14, v15, vcc
	v_sqrt_f32_e32 v15, v14
	s_nop 0
	v_add_u32_e32 v216, -1, v15
	v_add_u32_e32 v217, 1, v15
	v_fma_f32 v218, -v216, v15, v14
	v_fma_f32 v220, -v217, v15, v14
	v_cmp_ge_f32_e64 s[30:31], 0, v218
	s_nop 1
	v_cndmask_b32_e64 v15, v15, v216, s[30:31]
	v_cmp_lt_f32_e64 s[30:31], 0, v220
	s_nop 1
	v_cndmask_b32_e64 v15, v15, v217, s[30:31]
	v_mul_f32_e32 v216, 0x37800000, v15
	v_cndmask_b32_e32 v15, v15, v216, vcc
	v_cmp_class_f32_e32 vcc, v14, v222
	s_nop 1
	v_cndmask_b32_e32 v14, v15, v14, vcc
	v_div_scale_f32 v15, s[30:31], v14, v14, 1.0
	v_rcp_f32_e32 v216, v15
	v_div_scale_f32 v217, vcc, 1.0, v14, 1.0
	v_fma_f32 v218, -v15, v216, 1.0
	v_fmac_f32_e32 v216, v218, v216
	v_mul_f32_e32 v218, v217, v216
	v_fma_f32 v220, -v15, v218, v217
	v_fmac_f32_e32 v218, v220, v216
	v_fma_f32 v15, -v15, v218, v217
	v_div_fmas_f32 v15, v15, v216, v218
	v_div_fixup_f32 v14, v15, v14, 1.0
	s_mul_i32 s52, s9, 320
	s_lshl_b32 s53, s13, 5
	s_add_i32 s52, s52, s53
	s_add_i32 s52, s52, 0x800
	v_lshl_add_u32 v12, v13, 2, s52
	ds_write_b32 v12, v14
	s_lshl_b32 s53, s13, 3
	s_sub_i32 s53, 16, s53
	v_sub_u32_e32 v15, s53, v13
	v_cmp_ge_u32_e32 vcc, s12, v15
	s_nop 1
	v_cndmask_b32_e32 v14, 0, v14, vcc
	s_nop 1
	v_readlane_b32 s20, v14, 0
	v_readlane_b32 s21, v14, 1
	v_readlane_b32 s22, v14, 2
	v_readlane_b32 s23, v14, 3
	v_readlane_b32 s24, v14, 4
	v_readlane_b32 s25, v14, 5
	v_readlane_b32 s26, v14, 6
	v_readlane_b32 s27, v14, 7
	s_nop 1
	s_add_i32 s55, s14, 8
	s_add_i32 s52, s55, 0
	s_mov_b32 s53, 0
	s_lshl_b64 s[52:53], s[52:53], 14
	s_add_u32 s52, s52, s2
	s_addc_u32 s53, s53, s3
	global_load_dwordx4 v[80:83], v1, s[52:53]
	global_load_dwordx4 v[84:87], v1, s[52:53] offset:1024
	s_add_i32 s52, s55, 1
	s_mov_b32 s53, 0
	s_lshl_b64 s[52:53], s[52:53], 14
	s_add_u32 s52, s52, s2
	s_addc_u32 s53, s53, s3
	global_load_dwordx4 v[88:91], v1, s[52:53]
	global_load_dwordx4 v[92:95], v1, s[52:53] offset:1024
	s_add_i32 s52, s55, 2
	s_mov_b32 s53, 0
	s_lshl_b64 s[52:53], s[52:53], 14
	s_add_u32 s52, s52, s2
	s_addc_u32 s53, s53, s3
	global_load_dwordx4 v[96:99], v1, s[52:53]
	global_load_dwordx4 v[100:103], v1, s[52:53] offset:1024
	s_add_i32 s52, s55, 3
	s_mov_b32 s53, 0
	s_lshl_b64 s[52:53], s[52:53], 14
	s_add_u32 s52, s52, s2
	s_addc_u32 s53, s53, s3
	global_load_dwordx4 v[104:107], v1, s[52:53]
	global_load_dwordx4 v[108:111], v1, s[52:53] offset:1024
	s_add_i32 s52, s55, 4
	s_mov_b32 s53, 0
	s_lshl_b64 s[52:53], s[52:53], 14
	s_add_u32 s52, s52, s2
	s_addc_u32 s53, s53, s3
	global_load_dwordx4 v[112:115], v1, s[52:53]
	global_load_dwordx4 v[116:119], v1, s[52:53] offset:1024
	s_add_i32 s52, s55, 5
	s_mov_b32 s53, 0
	s_lshl_b64 s[52:53], s[52:53], 14
	s_add_u32 s52, s52, s2
	s_addc_u32 s53, s53, s3
	global_load_dwordx4 v[120:123], v1, s[52:53]
	global_load_dwordx4 v[124:127], v1, s[52:53] offset:1024
	s_add_i32 s52, s55, 6
	s_mov_b32 s53, 0
	s_lshl_b64 s[52:53], s[52:53], 14
	s_add_u32 s52, s52, s2
	s_addc_u32 s53, s53, s3
	global_load_dwordx4 v[128:131], v1, s[52:53]
	global_load_dwordx4 v[132:135], v1, s[52:53] offset:1024
	s_add_i32 s52, s55, 7
	s_mov_b32 s53, 0
	s_lshl_b64 s[52:53], s[52:53], 14
	s_add_u32 s52, s52, s2
	s_addc_u32 s53, s53, s3
	global_load_dwordx4 v[136:139], v1, s[52:53]
	global_load_dwordx4 v[140:143], v1, s[52:53] offset:1024
	v_mul_f32_e32 v16, s20, v16
	v_mul_f32_e32 v17, s20, v17
	v_mul_f32_e32 v18, s20, v18
	v_mul_f32_e32 v19, s20, v19
	v_mul_f32_e32 v20, s20, v20
	v_mul_f32_e32 v21, s20, v21
	v_mul_f32_e32 v22, s20, v22
	v_mul_f32_e32 v23, s20, v23
	v_pk_mul_f32 v[16:17], v[16:17], v[4:5]
	v_pk_mul_f32 v[18:19], v[18:19], v[6:7]
	v_pk_mul_f32 v[20:21], v[20:21], v[8:9]
	v_pk_mul_f32 v[22:23], v[22:23], v[10:11]
	v_mul_f32_e32 v24, s21, v24
	v_mul_f32_e32 v25, s21, v25
	v_mul_f32_e32 v26, s21, v26
	v_mul_f32_e32 v27, s21, v27
	v_mul_f32_e32 v28, s21, v28
	v_mul_f32_e32 v29, s21, v29
	v_mul_f32_e32 v30, s21, v30
	v_mul_f32_e32 v31, s21, v31
	v_pk_mul_f32 v[24:25], v[24:25], v[4:5]
	v_pk_mul_f32 v[26:27], v[26:27], v[6:7]
	v_pk_mul_f32 v[28:29], v[28:29], v[8:9]
	v_pk_mul_f32 v[30:31], v[30:31], v[10:11]
	v_mul_f32_e32 v32, s22, v32
	v_mul_f32_e32 v33, s22, v33
	v_mul_f32_e32 v34, s22, v34
	v_mul_f32_e32 v35, s22, v35
	v_mul_f32_e32 v36, s22, v36
	v_mul_f32_e32 v37, s22, v37
	v_mul_f32_e32 v38, s22, v38
	v_mul_f32_e32 v39, s22, v39
	v_pk_mul_f32 v[32:33], v[32:33], v[4:5]
	v_pk_mul_f32 v[34:35], v[34:35], v[6:7]
	v_pk_mul_f32 v[36:37], v[36:37], v[8:9]
	v_pk_mul_f32 v[38:39], v[38:39], v[10:11]
	v_mul_f32_e32 v40, s23, v40
	v_mul_f32_e32 v41, s23, v41
	v_mul_f32_e32 v42, s23, v42
	v_mul_f32_e32 v43, s23, v43
	v_mul_f32_e32 v44, s23, v44
	v_mul_f32_e32 v45, s23, v45
	v_mul_f32_e32 v46, s23, v46
	v_mul_f32_e32 v47, s23, v47
	v_pk_mul_f32 v[40:41], v[40:41], v[4:5]
	v_pk_mul_f32 v[42:43], v[42:43], v[6:7]
	v_pk_mul_f32 v[44:45], v[44:45], v[8:9]
	v_pk_mul_f32 v[46:47], v[46:47], v[10:11]
	v_mul_f32_e32 v48, s24, v48
	v_mul_f32_e32 v49, s24, v49
	v_mul_f32_e32 v50, s24, v50
	v_mul_f32_e32 v51, s24, v51
	v_mul_f32_e32 v52, s24, v52
	v_mul_f32_e32 v53, s24, v53
	v_mul_f32_e32 v54, s24, v54
	v_mul_f32_e32 v55, s24, v55
	v_pk_mul_f32 v[48:49], v[48:49], v[4:5]
	v_pk_mul_f32 v[50:51], v[50:51], v[6:7]
	v_pk_mul_f32 v[52:53], v[52:53], v[8:9]
	v_pk_mul_f32 v[54:55], v[54:55], v[10:11]
	v_mul_f32_e32 v56, s25, v56
	v_mul_f32_e32 v57, s25, v57
	v_mul_f32_e32 v58, s25, v58
	v_mul_f32_e32 v59, s25, v59
	v_mul_f32_e32 v60, s25, v60
	v_mul_f32_e32 v61, s25, v61
	v_mul_f32_e32 v62, s25, v62
	v_mul_f32_e32 v63, s25, v63
	v_pk_mul_f32 v[56:57], v[56:57], v[4:5]
	v_pk_mul_f32 v[58:59], v[58:59], v[6:7]
	v_pk_mul_f32 v[60:61], v[60:61], v[8:9]
	v_pk_mul_f32 v[62:63], v[62:63], v[10:11]
	v_mul_f32_e32 v64, s26, v64
	v_mul_f32_e32 v65, s26, v65
	v_mul_f32_e32 v66, s26, v66
	v_mul_f32_e32 v67, s26, v67
	v_mul_f32_e32 v68, s26, v68
	v_mul_f32_e32 v69, s26, v69
	v_mul_f32_e32 v70, s26, v70
	v_mul_f32_e32 v71, s26, v71
	v_pk_mul_f32 v[64:65], v[64:65], v[4:5]
	v_pk_mul_f32 v[66:67], v[66:67], v[6:7]
	v_pk_mul_f32 v[68:69], v[68:69], v[8:9]
	v_pk_mul_f32 v[70:71], v[70:71], v[10:11]
	v_mul_f32_e32 v72, s27, v72
	v_mul_f32_e32 v73, s27, v73
	v_mul_f32_e32 v74, s27, v74
	v_mul_f32_e32 v75, s27, v75
	v_mul_f32_e32 v76, s27, v76
	v_mul_f32_e32 v77, s27, v77
	v_mul_f32_e32 v78, s27, v78
	v_mul_f32_e32 v79, s27, v79
	v_pk_mul_f32 v[72:73], v[72:73], v[4:5]
	v_pk_mul_f32 v[74:75], v[74:75], v[6:7]
	v_pk_mul_f32 v[76:77], v[76:77], v[8:9]
	v_pk_mul_f32 v[78:79], v[78:79], v[10:11]
	v_pk_add_f32 v[208:209], v[208:209], v[16:17]
	v_pk_add_f32 v[210:211], v[210:211], v[18:19]
	v_pk_add_f32 v[212:213], v[212:213], v[20:21]
	v_pk_add_f32 v[214:215], v[214:215], v[22:23]
	v_pk_add_f32 v[208:209], v[208:209], v[24:25]
	v_pk_add_f32 v[210:211], v[210:211], v[26:27]
	v_pk_add_f32 v[212:213], v[212:213], v[28:29]
	v_pk_add_f32 v[214:215], v[214:215], v[30:31]
	v_pk_add_f32 v[208:209], v[208:209], v[32:33]
	v_pk_add_f32 v[210:211], v[210:211], v[34:35]
	v_pk_add_f32 v[212:213], v[212:213], v[36:37]
	v_pk_add_f32 v[214:215], v[214:215], v[38:39]
	v_pk_add_f32 v[208:209], v[208:209], v[40:41]
	v_pk_add_f32 v[210:211], v[210:211], v[42:43]
	v_pk_add_f32 v[212:213], v[212:213], v[44:45]
	v_pk_add_f32 v[214:215], v[214:215], v[46:47]
	v_pk_add_f32 v[208:209], v[208:209], v[48:49]
	v_pk_add_f32 v[210:211], v[210:211], v[50:51]
	v_pk_add_f32 v[212:213], v[212:213], v[52:53]
	v_pk_add_f32 v[214:215], v[214:215], v[54:55]
	v_pk_add_f32 v[208:209], v[208:209], v[56:57]
	v_pk_add_f32 v[210:211], v[210:211], v[58:59]
	v_pk_add_f32 v[212:213], v[212:213], v[60:61]
	v_pk_add_f32 v[214:215], v[214:215], v[62:63]
	v_pk_add_f32 v[208:209], v[208:209], v[64:65]
	v_pk_add_f32 v[210:211], v[210:211], v[66:67]
	v_pk_add_f32 v[212:213], v[212:213], v[68:69]
	v_pk_add_f32 v[214:215], v[214:215], v[70:71]
	v_pk_add_f32 v[208:209], v[208:209], v[72:73]
	v_pk_add_f32 v[210:211], v[210:211], v[74:75]
	v_pk_add_f32 v[212:213], v[212:213], v[76:77]
	v_pk_add_f32 v[214:215], v[214:215], v[78:79]
	s_add_i32 s13, s13, 1
	s_add_i32 s14, s14, 8
	s_add_i32 s15, s15, 8
	s_waitcnt vmcnt(0)
	v_mul_f32_e32 v16, v80, v80
	v_fmac_f32_e32 v16, v81, v81
	v_fmac_f32_e32 v16, v82, v82
	v_fmac_f32_e32 v16, v83, v83
	v_fmac_f32_e32 v16, v84, v84
	v_fmac_f32_e32 v16, v85, v85
	v_fmac_f32_e32 v16, v86, v86
	v_fmac_f32_e32 v16, v87, v87
	v_mul_f32_e32 v17, v88, v88
	v_fmac_f32_e32 v17, v89, v89
	v_fmac_f32_e32 v17, v90, v90
	v_fmac_f32_e32 v17, v91, v91
	v_fmac_f32_e32 v17, v92, v92
	v_fmac_f32_e32 v17, v93, v93
	v_fmac_f32_e32 v17, v94, v94
	v_fmac_f32_e32 v17, v95, v95
	v_mul_f32_e32 v18, v96, v96
	v_fmac_f32_e32 v18, v97, v97
	v_fmac_f32_e32 v18, v98, v98
	v_fmac_f32_e32 v18, v99, v99
	v_fmac_f32_e32 v18, v100, v100
	v_fmac_f32_e32 v18, v101, v101
	v_fmac_f32_e32 v18, v102, v102
	v_fmac_f32_e32 v18, v103, v103
	v_mul_f32_e32 v19, v104, v104
	v_fmac_f32_e32 v19, v105, v105
	v_fmac_f32_e32 v19, v106, v106
	v_fmac_f32_e32 v19, v107, v107
	v_fmac_f32_e32 v19, v108, v108
	v_fmac_f32_e32 v19, v109, v109
	v_fmac_f32_e32 v19, v110, v110
	v_fmac_f32_e32 v19, v111, v111
	v_mul_f32_e32 v20, v112, v112
	v_fmac_f32_e32 v20, v113, v113
	v_fmac_f32_e32 v20, v114, v114
	v_fmac_f32_e32 v20, v115, v115
	v_fmac_f32_e32 v20, v116, v116
	v_fmac_f32_e32 v20, v117, v117
	v_fmac_f32_e32 v20, v118, v118
	v_fmac_f32_e32 v20, v119, v119
	v_mul_f32_e32 v21, v120, v120
	v_fmac_f32_e32 v21, v121, v121
	v_fmac_f32_e32 v21, v122, v122
	v_fmac_f32_e32 v21, v123, v123
	v_fmac_f32_e32 v21, v124, v124
	v_fmac_f32_e32 v21, v125, v125
	v_fmac_f32_e32 v21, v126, v126
	v_fmac_f32_e32 v21, v127, v127
	v_mul_f32_e32 v22, v128, v128
	v_fmac_f32_e32 v22, v129, v129
	v_fmac_f32_e32 v22, v130, v130
	v_fmac_f32_e32 v22, v131, v131
	v_fmac_f32_e32 v22, v132, v132
	v_fmac_f32_e32 v22, v133, v133
	v_fmac_f32_e32 v22, v134, v134
	v_fmac_f32_e32 v22, v135, v135
	v_mul_f32_e32 v23, v136, v136
	v_fmac_f32_e32 v23, v137, v137
	v_fmac_f32_e32 v23, v138, v138
	v_fmac_f32_e32 v23, v139, v139
	v_fmac_f32_e32 v23, v140, v140
	v_fmac_f32_e32 v23, v141, v141
	v_fmac_f32_e32 v23, v142, v142
	v_fmac_f32_e32 v23, v143, v143
	s_nop 1
	v_add_f32_dpp v16, v16, v16 quad_perm:[1,0,3,2] row_mask:0xf bank_mask:0xf bound_ctrl:1
	v_add_f32_dpp v17, v17, v17 quad_perm:[1,0,3,2] row_mask:0xf bank_mask:0xf bound_ctrl:1
	v_add_f32_dpp v18, v18, v18 quad_perm:[1,0,3,2] row_mask:0xf bank_mask:0xf bound_ctrl:1
	v_add_f32_dpp v19, v19, v19 quad_perm:[1,0,3,2] row_mask:0xf bank_mask:0xf bound_ctrl:1
	v_add_f32_dpp v20, v20, v20 quad_perm:[1,0,3,2] row_mask:0xf bank_mask:0xf bound_ctrl:1
	v_add_f32_dpp v21, v21, v21 quad_perm:[1,0,3,2] row_mask:0xf bank_mask:0xf bound_ctrl:1
	v_add_f32_dpp v22, v22, v22 quad_perm:[1,0,3,2] row_mask:0xf bank_mask:0xf bound_ctrl:1
	v_add_f32_dpp v23, v23, v23 quad_perm:[1,0,3,2] row_mask:0xf bank_mask:0xf bound_ctrl:1
	s_nop 1
	v_add_f32_dpp v16, v16, v16 quad_perm:[2,3,0,1] row_mask:0xf bank_mask:0xf bound_ctrl:1
	v_add_f32_dpp v17, v17, v17 quad_perm:[2,3,0,1] row_mask:0xf bank_mask:0xf bound_ctrl:1
	v_add_f32_dpp v18, v18, v18 quad_perm:[2,3,0,1] row_mask:0xf bank_mask:0xf bound_ctrl:1
	v_add_f32_dpp v19, v19, v19 quad_perm:[2,3,0,1] row_mask:0xf bank_mask:0xf bound_ctrl:1
	v_add_f32_dpp v20, v20, v20 quad_perm:[2,3,0,1] row_mask:0xf bank_mask:0xf bound_ctrl:1
	v_add_f32_dpp v21, v21, v21 quad_perm:[2,3,0,1] row_mask:0xf bank_mask:0xf bound_ctrl:1
	v_add_f32_dpp v22, v22, v22 quad_perm:[2,3,0,1] row_mask:0xf bank_mask:0xf bound_ctrl:1
	v_add_f32_dpp v23, v23, v23 quad_perm:[2,3,0,1] row_mask:0xf bank_mask:0xf bound_ctrl:1
	s_nop 1
	v_add_f32_dpp v16, v16, v16 row_half_mirror row_mask:0xf bank_mask:0xf bound_ctrl:1
	v_add_f32_dpp v17, v17, v17 row_half_mirror row_mask:0xf bank_mask:0xf bound_ctrl:1
	v_add_f32_dpp v18, v18, v18 row_half_mirror row_mask:0xf bank_mask:0xf bound_ctrl:1
	v_add_f32_dpp v19, v19, v19 row_half_mirror row_mask:0xf bank_mask:0xf bound_ctrl:1
	v_add_f32_dpp v20, v20, v20 row_half_mirror row_mask:0xf bank_mask:0xf bound_ctrl:1
	v_add_f32_dpp v21, v21, v21 row_half_mirror row_mask:0xf bank_mask:0xf bound_ctrl:1
	v_add_f32_dpp v22, v22, v22 row_half_mirror row_mask:0xf bank_mask:0xf bound_ctrl:1
	v_add_f32_dpp v23, v23, v23 row_half_mirror row_mask:0xf bank_mask:0xf bound_ctrl:1
	s_nop 1
	v_add_f32_dpp v16, v16, v16 row_mirror row_mask:0xf bank_mask:0xf bound_ctrl:1
	v_add_f32_dpp v17, v17, v17 row_mirror row_mask:0xf bank_mask:0xf bound_ctrl:1
	v_add_f32_dpp v18, v18, v18 row_mirror row_mask:0xf bank_mask:0xf bound_ctrl:1
	v_add_f32_dpp v19, v19, v19 row_mirror row_mask:0xf bank_mask:0xf bound_ctrl:1
	v_add_f32_dpp v20, v20, v20 row_mirror row_mask:0xf bank_mask:0xf bound_ctrl:1
	v_add_f32_dpp v21, v21, v21 row_mirror row_mask:0xf bank_mask:0xf bound_ctrl:1
	v_add_f32_dpp v22, v22, v22 row_mirror row_mask:0xf bank_mask:0xf bound_ctrl:1
	v_add_f32_dpp v23, v23, v23 row_mirror row_mask:0xf bank_mask:0xf bound_ctrl:1
	v_lshrrev_b32_e32 v12, 6, v1
	v_and_b32_e32 v12, 12, v12
	s_lshl_b32 s52, s9, 4
	s_add_i32 s52, s52, 1024
	v_add_u32_e32 v12, s52, v12
	s_mov_b32 exec_lo, 0x10001
	s_mov_b32 exec_hi, 0x10001
	ds_write_b32 v12, v16
	ds_write_b32 v12, v17 offset:128
	ds_write_b32 v12, v18 offset:256
	ds_write_b32 v12, v19 offset:384
	ds_write_b32 v12, v20 offset:512
	ds_write_b32 v12, v21 offset:640
	ds_write_b32 v12, v22 offset:768
	ds_write_b32 v12, v23 offset:896
	s_mov_b64 exec, -1
	s_waitcnt lgkmcnt(0)
	s_barrier
	v_lshrrev_b32_e32 v13, 4, v1
	v_and_b32_e32 v13, 7, v13
	v_lshlrev_b32_e32 v12, 7, v13
	v_add_u32_e32 v12, 0x400, v12
	ds_read_b128 v[24:27], v12
	ds_read_b128 v[28:31], v12 offset:16
	ds_read_b128 v[32:35], v12 offset:32
	ds_read_b128 v[36:39], v12 offset:48
	ds_read_b128 v[40:43], v12 offset:64
	ds_read_b128 v[44:47], v12 offset:80
	ds_read_b128 v[48:51], v12 offset:96
	ds_read_b128 v[52:55], v12 offset:112
	s_waitcnt lgkmcnt(0)
	v_add_f32_e32 v14, v24, v25
	v_add_f32_e32 v14, v14, v26
	v_add_f32_e32 v14, v14, v27
	v_add_f32_e32 v14, v14, v28
	v_add_f32_e32 v14, v14, v29
	v_add_f32_e32 v14, v14, v30
	v_add_f32_e32 v14, v14, v31
	v_add_f32_e32 v14, v14, v32
	v_add_f32_e32 v14, v14, v33
	v_add_f32_e32 v14, v14, v34
	v_add_f32_e32 v14, v14, v35
	v_add_f32_e32 v14, v14, v36
	v_add_f32_e32 v14, v14, v37
	v_add_f32_e32 v14, v14, v38
	v_add_f32_e32 v14, v14, v39
	v_add_f32_e32 v14, v14, v40
	v_add_f32_e32 v14, v14, v41
	v_add_f32_e32 v14, v14, v42
	v_add_f32_e32 v14, v14, v43
	v_add_f32_e32 v14, v14, v44
	v_add_f32_e32 v14, v14, v45
	v_add_f32_e32 v14, v14, v46
	v_add_f32_e32 v14, v14, v47
	v_add_f32_e32 v14, v14, v48
	v_add_f32_e32 v14, v14, v49
	v_add_f32_e32 v14, v14, v50
	v_add_f32_e32 v14, v14, v51
	v_add_f32_e32 v14, v14, v52
	v_add_f32_e32 v14, v14, v53
	v_add_f32_e32 v14, v14, v54
	v_add_f32_e32 v14, v14, v55
	v_mov_b32_e32 v221, 0x358637bd
	v_mov_b32_e32 v222, 0x260
	s_mov_b32 s54, 0xf800000
	v_fmamk_f32 v14, v14, 0x39800000, v221
	v_mul_f32_e32 v15, 0x4f800000, v14
	v_cmp_gt_f32_e32 vcc, s54, v14
	s_nop 1
	v_cndmask_b32_e32 v14, v14, v15, vcc
	v_sqrt_f32_e32 v15, v14
	s_nop 0
	v_add_u32_e32 v216, -1, v15
	v_add_u32_e32 v217, 1, v15
	v_fma_f32 v218, -v216, v15, v14
	v_fma_f32 v220, -v217, v15, v14
	v_cmp_ge_f32_e64 s[30:31], 0, v218
	s_nop 1
	v_cndmask_b32_e64 v15, v15, v216, s[30:31]
	v_cmp_lt_f32_e64 s[30:31], 0, v220
	s_nop 1
	v_cndmask_b32_e64 v15, v15, v217, s[30:31]
	v_mul_f32_e32 v216, 0x37800000, v15
	v_cndmask_b32_e32 v15, v15, v216, vcc
	v_cmp_class_f32_e32 vcc, v14, v222
	s_nop 1
	v_cndmask_b32_e32 v14, v15, v14, vcc
	v_div_scale_f32 v15, s[30:31], v14, v14, 1.0
	v_rcp_f32_e32 v216, v15
	v_div_scale_f32 v217, vcc, 1.0, v14, 1.0
	v_fma_f32 v218, -v15, v216, 1.0
	v_fmac_f32_e32 v216, v218, v216
	v_mul_f32_e32 v218, v217, v216
	v_fma_f32 v220, -v15, v218, v217
	v_fmac_f32_e32 v218, v220, v216
	v_fma_f32 v15, -v15, v218, v217
	v_div_fmas_f32 v15, v15, v216, v218
	v_div_fixup_f32 v14, v15, v14, 1.0
	s_mul_i32 s52, s9, 320
	s_lshl_b32 s53, s13, 5
	s_add_i32 s52, s52, s53
	s_add_i32 s52, s52, 0x800
	v_lshl_add_u32 v12, v13, 2, s52
	ds_write_b32 v12, v14
	s_lshl_b32 s53, s13, 3
	s_sub_i32 s53, 16, s53
	v_sub_u32_e32 v15, s53, v13
	v_cmp_ge_u32_e32 vcc, s12, v15
	s_nop 1
	v_cndmask_b32_e32 v14, 0, v14, vcc
	s_nop 1
	v_readlane_b32 s20, v14, 0
	v_readlane_b32 s21, v14, 1
	v_readlane_b32 s22, v14, 2
	v_readlane_b32 s23, v14, 3
	v_readlane_b32 s24, v14, 4
	v_readlane_b32 s25, v14, 5
	v_readlane_b32 s26, v14, 6
	v_readlane_b32 s27, v14, 7
	s_nop 1
	s_add_i32 s55, s14, 8
	s_add_i32 s52, s55, 0
	s_mov_b32 s53, 0
	s_lshl_b64 s[52:53], s[52:53], 14
	s_add_u32 s52, s52, s2
	s_addc_u32 s53, s53, s3
	global_load_dwordx4 v[16:19], v1, s[52:53]
	global_load_dwordx4 v[20:23], v1, s[52:53] offset:1024
	s_add_i32 s52, s55, 1
	s_mov_b32 s53, 0
	s_lshl_b64 s[52:53], s[52:53], 14
	s_add_u32 s52, s52, s2
	s_addc_u32 s53, s53, s3
	global_load_dwordx4 v[24:27], v1, s[52:53]
	global_load_dwordx4 v[28:31], v1, s[52:53] offset:1024
	s_add_i32 s52, s55, 2
	s_mov_b32 s53, 0
	s_lshl_b64 s[52:53], s[52:53], 14
	s_add_u32 s52, s52, s2
	s_addc_u32 s53, s53, s3
	global_load_dwordx4 v[32:35], v1, s[52:53]
	global_load_dwordx4 v[36:39], v1, s[52:53] offset:1024
	s_add_i32 s52, s55, 3
	s_mov_b32 s53, 0
	s_lshl_b64 s[52:53], s[52:53], 14
	s_add_u32 s52, s52, s2
	s_addc_u32 s53, s53, s3
	global_load_dwordx4 v[40:43], v1, s[52:53]
	global_load_dwordx4 v[44:47], v1, s[52:53] offset:1024
	s_add_i32 s52, s55, 4
	s_mov_b32 s53, 0
	s_lshl_b64 s[52:53], s[52:53], 14
	s_add_u32 s52, s52, s2
	s_addc_u32 s53, s53, s3
	global_load_dwordx4 v[48:51], v1, s[52:53]
	global_load_dwordx4 v[52:55], v1, s[52:53] offset:1024
	s_add_i32 s52, s55, 5
	s_mov_b32 s53, 0
	s_lshl_b64 s[52:53], s[52:53], 14
	s_add_u32 s52, s52, s2
	s_addc_u32 s53, s53, s3
	global_load_dwordx4 v[56:59], v1, s[52:53]
	global_load_dwordx4 v[60:63], v1, s[52:53] offset:1024
	s_add_i32 s52, s55, 6
	s_mov_b32 s53, 0
	s_lshl_b64 s[52:53], s[52:53], 14
	s_add_u32 s52, s52, s2
	s_addc_u32 s53, s53, s3
	global_load_dwordx4 v[64:67], v1, s[52:53]
	global_load_dwordx4 v[68:71], v1, s[52:53] offset:1024
	s_add_i32 s52, s55, 7
	s_mov_b32 s53, 0
	s_lshl_b64 s[52:53], s[52:53], 14
	s_add_u32 s52, s52, s2
	s_addc_u32 s53, s53, s3
	global_load_dwordx4 v[72:75], v1, s[52:53]
	global_load_dwordx4 v[76:79], v1, s[52:53] offset:1024
	v_mul_f32_e32 v80, s20, v80
	v_mul_f32_e32 v81, s20, v81
	v_mul_f32_e32 v82, s20, v82
	v_mul_f32_e32 v83, s20, v83
	v_mul_f32_e32 v84, s20, v84
	v_mul_f32_e32 v85, s20, v85
	v_mul_f32_e32 v86, s20, v86
	v_mul_f32_e32 v87, s20, v87
	v_pk_mul_f32 v[80:81], v[80:81], v[4:5]
	v_pk_mul_f32 v[82:83], v[82:83], v[6:7]
	v_pk_mul_f32 v[84:85], v[84:85], v[8:9]
	v_pk_mul_f32 v[86:87], v[86:87], v[10:11]
	v_mul_f32_e32 v88, s21, v88
	v_mul_f32_e32 v89, s21, v89
	v_mul_f32_e32 v90, s21, v90
	v_mul_f32_e32 v91, s21, v91
	v_mul_f32_e32 v92, s21, v92
	v_mul_f32_e32 v93, s21, v93
	v_mul_f32_e32 v94, s21, v94
	v_mul_f32_e32 v95, s21, v95
	v_pk_mul_f32 v[88:89], v[88:89], v[4:5]
	v_pk_mul_f32 v[90:91], v[90:91], v[6:7]
	v_pk_mul_f32 v[92:93], v[92:93], v[8:9]
	v_pk_mul_f32 v[94:95], v[94:95], v[10:11]
	v_mul_f32_e32 v96, s22, v96
	v_mul_f32_e32 v97, s22, v97
	v_mul_f32_e32 v98, s22, v98
	v_mul_f32_e32 v99, s22, v99
	v_mul_f32_e32 v100, s22, v100
	v_mul_f32_e32 v101, s22, v101
	v_mul_f32_e32 v102, s22, v102
	v_mul_f32_e32 v103, s22, v103
	v_pk_mul_f32 v[96:97], v[96:97], v[4:5]
	v_pk_mul_f32 v[98:99], v[98:99], v[6:7]
	v_pk_mul_f32 v[100:101], v[100:101], v[8:9]
	v_pk_mul_f32 v[102:103], v[102:103], v[10:11]
	v_mul_f32_e32 v104, s23, v104
	v_mul_f32_e32 v105, s23, v105
	v_mul_f32_e32 v106, s23, v106
	v_mul_f32_e32 v107, s23, v107
	v_mul_f32_e32 v108, s23, v108
	v_mul_f32_e32 v109, s23, v109
	v_mul_f32_e32 v110, s23, v110
	v_mul_f32_e32 v111, s23, v111
	v_pk_mul_f32 v[104:105], v[104:105], v[4:5]
	v_pk_mul_f32 v[106:107], v[106:107], v[6:7]
	v_pk_mul_f32 v[108:109], v[108:109], v[8:9]
	v_pk_mul_f32 v[110:111], v[110:111], v[10:11]
	v_mul_f32_e32 v112, s24, v112
	v_mul_f32_e32 v113, s24, v113
	v_mul_f32_e32 v114, s24, v114
	v_mul_f32_e32 v115, s24, v115
	v_mul_f32_e32 v116, s24, v116
	v_mul_f32_e32 v117, s24, v117
	v_mul_f32_e32 v118, s24, v118
	v_mul_f32_e32 v119, s24, v119
	v_pk_mul_f32 v[112:113], v[112:113], v[4:5]
	v_pk_mul_f32 v[114:115], v[114:115], v[6:7]
	v_pk_mul_f32 v[116:117], v[116:117], v[8:9]
	v_pk_mul_f32 v[118:119], v[118:119], v[10:11]
	v_mul_f32_e32 v120, s25, v120
	v_mul_f32_e32 v121, s25, v121
	v_mul_f32_e32 v122, s25, v122
	v_mul_f32_e32 v123, s25, v123
	v_mul_f32_e32 v124, s25, v124
	v_mul_f32_e32 v125, s25, v125
	v_mul_f32_e32 v126, s25, v126
	v_mul_f32_e32 v127, s25, v127
	v_pk_mul_f32 v[120:121], v[120:121], v[4:5]
	v_pk_mul_f32 v[122:123], v[122:123], v[6:7]
	v_pk_mul_f32 v[124:125], v[124:125], v[8:9]
	v_pk_mul_f32 v[126:127], v[126:127], v[10:11]
	v_mul_f32_e32 v128, s26, v128
	v_mul_f32_e32 v129, s26, v129
	v_mul_f32_e32 v130, s26, v130
	v_mul_f32_e32 v131, s26, v131
	v_mul_f32_e32 v132, s26, v132
	v_mul_f32_e32 v133, s26, v133
	v_mul_f32_e32 v134, s26, v134
	v_mul_f32_e32 v135, s26, v135
	v_pk_mul_f32 v[128:129], v[128:129], v[4:5]
	v_pk_mul_f32 v[130:131], v[130:131], v[6:7]
	v_pk_mul_f32 v[132:133], v[132:133], v[8:9]
	v_pk_mul_f32 v[134:135], v[134:135], v[10:11]
	v_mul_f32_e32 v136, s27, v136
	v_mul_f32_e32 v137, s27, v137
	v_mul_f32_e32 v138, s27, v138
	v_mul_f32_e32 v139, s27, v139
	v_mul_f32_e32 v140, s27, v140
	v_mul_f32_e32 v141, s27, v141
	v_mul_f32_e32 v142, s27, v142
	v_mul_f32_e32 v143, s27, v143
	v_pk_mul_f32 v[136:137], v[136:137], v[4:5]
	v_pk_mul_f32 v[138:139], v[138:139], v[6:7]
	v_pk_mul_f32 v[140:141], v[140:141], v[8:9]
	v_pk_mul_f32 v[142:143], v[142:143], v[10:11]
	v_pk_add_f32 v[208:209], v[208:209], v[80:81]
	v_pk_add_f32 v[210:211], v[210:211], v[82:83]
	v_pk_add_f32 v[212:213], v[212:213], v[84:85]
	v_pk_add_f32 v[214:215], v[214:215], v[86:87]
	v_pk_add_f32 v[208:209], v[208:209], v[88:89]
	v_pk_add_f32 v[210:211], v[210:211], v[90:91]
	v_pk_add_f32 v[212:213], v[212:213], v[92:93]
	v_pk_add_f32 v[214:215], v[214:215], v[94:95]
	v_pk_add_f32 v[208:209], v[208:209], v[96:97]
	v_pk_add_f32 v[210:211], v[210:211], v[98:99]
	v_pk_add_f32 v[212:213], v[212:213], v[100:101]
	v_pk_add_f32 v[214:215], v[214:215], v[102:103]
	v_pk_add_f32 v[208:209], v[208:209], v[104:105]
	v_pk_add_f32 v[210:211], v[210:211], v[106:107]
	v_pk_add_f32 v[212:213], v[212:213], v[108:109]
	v_pk_add_f32 v[214:215], v[214:215], v[110:111]
	v_pk_add_f32 v[208:209], v[208:209], v[112:113]
	v_pk_add_f32 v[210:211], v[210:211], v[114:115]
	v_pk_add_f32 v[212:213], v[212:213], v[116:117]
	v_pk_add_f32 v[214:215], v[214:215], v[118:119]
	v_pk_add_f32 v[208:209], v[208:209], v[120:121]
	v_pk_add_f32 v[210:211], v[210:211], v[122:123]
	v_pk_add_f32 v[212:213], v[212:213], v[124:125]
	v_pk_add_f32 v[214:215], v[214:215], v[126:127]
	v_pk_add_f32 v[208:209], v[208:209], v[128:129]
	v_pk_add_f32 v[210:211], v[210:211], v[130:131]
	v_pk_add_f32 v[212:213], v[212:213], v[132:133]
	v_pk_add_f32 v[214:215], v[214:215], v[134:135]
	v_pk_add_f32 v[208:209], v[208:209], v[136:137]
	v_pk_add_f32 v[210:211], v[210:211], v[138:139]
	v_pk_add_f32 v[212:213], v[212:213], v[140:141]
	v_pk_add_f32 v[214:215], v[214:215], v[142:143]
	s_add_i32 s13, s13, 1
	s_add_i32 s14, s14, 8
	s_add_i32 s15, s15, 8
	s_branch .Lp1f_main
